# attention unit prologue: 32-lane max of the cut distance via DPP row ops instead of five ds_bpermute hops
# baseline (speedup 1.0000x reference)
.LBB0_520:
	v_mov_b32_e32 v218, v3
	s_and_b32 s56, s60, 0xffffff80
	s_sub_i32 s79, s66, s56
	s_lshl_b32 s4, s60, 8
	v_add_u32_e32 v184, s79, v198
	s_and_b32 s8, s4, 0x7800
	v_ashrrev_i32_e32 v185, 31, v184
	v_lshl_add_u64 v[182:183], v[184:185], 0, s[8:9]
	s_and_b32 s78, s60, 7
	v_lshlrev_b64 v[4:5], 11, v[182:183]
	v_lshl_add_u64 v[4:5], s[38:39], 0, v[4:5]
	s_lshl_b32 s4, s78, 8
	s_mov_b32 s5, s9
	v_lshl_add_u64 v[4:5], v[4:5], 0, s[4:5]
	v_lshl_add_u64 v[4:5], v[4:5], 0, s[14:15]
	v_mov_b32_e32 v179, v3
	v_lshl_add_u64 v[4:5], v[4:5], 0, v[178:179]
	global_load_dwordx4 v[114:117], v[4:5], off
	global_load_dwordx4 v[118:121], v[4:5], off offset:32
	global_load_dwordx4 v[122:125], v[4:5], off offset:64
	global_load_dwordx4 v[126:129], v[4:5], off offset:96
	s_add_i32 s5, s78, 1
	s_ashr_i32 s57, s60, 6
	v_cvt_f32_ubyte0_e32 v18, s5
	s_and_b32 s58, s57, -2
	v_cmp_lt_f32_e32 vcc, s72, v18
	s_and_b64 s[60:61], vcc, exec
	s_cselect_b32 s59, 0xffffffc0, 0
	s_lshl_b32 s5, s8, 11
	s_add_u32 s8, s63, s5
	s_addc_u32 s61, s64, 0
	s_add_u32 s60, s8, s4
	s_addc_u32 s61, s61, 0
	s_add_u32 s5, s65, s5
	s_addc_u32 s8, s70, 0
	s_add_u32 s4, s5, s4
	s_addc_u32 s5, s8, 0
	s_sub_i32 s8, 31, s58
	v_mov_b32_e32 v181, v3
	v_lshl_or_b32 v2, s8, 6, v199
	v_lshl_add_u64 v[186:187], s[60:61], 0, v[180:181]
	v_lshlrev_b64 v[6:7], 11, v[2:3]
	s_lshl_b32 s60, s58, 6
	v_lshl_add_u64 v[8:9], v[186:187], 0, v[6:7]
	v_cndmask_b32_e32 v19, 0, v215, vcc
	v_lshl_add_u64 v[188:189], s[4:5], 0, v[180:181]
	v_subrev_u32_e32 v4, s60, v199
	v_add_co_u32_e32 v12, vcc, s73, v8
	v_add_u32_e32 v2, 0x780, v4
	v_lshl_add_u64 v[6:7], v[188:189], 0, v[6:7]
	v_addc_co_u32_e32 v13, vcc, 0, v9, vcc
	v_lshlrev_b64 v[10:11], 11, v[2:3]
	v_add_co_u32_e32 v14, vcc, s73, v6
	v_lshl_add_u64 v[16:17], v[186:187], 0, v[10:11]
	s_nop 0
	v_addc_co_u32_e32 v15, vcc, 0, v7, vcc
	global_load_dwordx4 v[134:137], v[8:9], off
	global_load_dwordx4 v[154:157], v[12:13], off
	global_load_dwordx4 v[146:149], v[6:7], off
	global_load_dwordx4 v[158:161], v[14:15], off
	v_add_co_u32_e32 v6, vcc, s73, v16
	v_lshl_add_u64 v[10:11], v[188:189], 0, v[10:11]
	s_nop 0
	v_addc_co_u32_e32 v7, vcc, 0, v17, vcc
	v_add_co_u32_e32 v8, vcc, s73, v10
	s_waitcnt vmcnt(7)
	v_and_b32_e32 v5, 0xffff0000, v114
	v_lshlrev_b32_e32 v2, 16, v114
	v_mul_f32_e32 v5, v5, v5
	v_addc_co_u32_e32 v9, vcc, 0, v11, vcc
	global_load_dwordx4 v[130:133], v[16:17], off
	global_load_dwordx4 v[142:145], v[6:7], off
	global_load_dwordx4 v[138:141], v[10:11], off
	global_load_dwordx4 v[150:153], v[8:9], off
	v_lshlrev_b32_e32 v6, 16, v115
	v_fmac_f32_e32 v5, v2, v2
	v_and_b32_e32 v7, 0xffff0000, v115
	v_fmac_f32_e32 v5, v6, v6
	v_lshlrev_b32_e32 v8, 16, v116
	v_fmac_f32_e32 v5, v7, v7
	v_and_b32_e32 v9, 0xffff0000, v116
	v_fmac_f32_e32 v5, v8, v8
	v_lshlrev_b32_e32 v10, 16, v117
	v_fmac_f32_e32 v5, v9, v9
	v_and_b32_e32 v11, 0xffff0000, v117
	v_fmac_f32_e32 v5, v10, v10
	s_waitcnt vmcnt(10)
	v_lshlrev_b32_e32 v12, 16, v118
	v_fmac_f32_e32 v5, v11, v11
	v_and_b32_e32 v13, 0xffff0000, v118
	v_fmac_f32_e32 v5, v12, v12
	v_lshlrev_b32_e32 v14, 16, v119
	v_fmac_f32_e32 v5, v13, v13
	v_and_b32_e32 v15, 0xffff0000, v119
	v_fmac_f32_e32 v5, v14, v14
	v_lshlrev_b32_e32 v16, 16, v120
	v_fmac_f32_e32 v5, v15, v15
	v_and_b32_e32 v17, 0xffff0000, v120
	v_fmac_f32_e32 v5, v16, v16
	v_lshlrev_b32_e32 v20, 16, v121
	v_fmac_f32_e32 v5, v17, v17
	v_and_b32_e32 v21, 0xffff0000, v121
	v_fmac_f32_e32 v5, v20, v20
	v_fmac_f32_e32 v5, v21, v21
	s_waitcnt vmcnt(9)
	v_lshlrev_b32_e32 v2, 16, v122
	v_fmac_f32_e32 v5, v2, v2
	v_and_b32_e32 v2, 0xffff0000, v122
	v_fmac_f32_e32 v5, v2, v2
	v_lshlrev_b32_e32 v2, 16, v123
	v_fmac_f32_e32 v5, v2, v2
	v_and_b32_e32 v2, 0xffff0000, v123
	v_fmac_f32_e32 v5, v2, v2
	v_lshlrev_b32_e32 v2, 16, v124
	v_fmac_f32_e32 v5, v2, v2
	v_and_b32_e32 v2, 0xffff0000, v124
	v_fmac_f32_e32 v5, v2, v2
	v_lshlrev_b32_e32 v2, 16, v125
	v_fmac_f32_e32 v5, v2, v2
	v_and_b32_e32 v2, 0xffff0000, v125
	v_fmac_f32_e32 v5, v2, v2
	s_waitcnt vmcnt(8)
	v_lshlrev_b32_e32 v2, 16, v126
	v_fmac_f32_e32 v5, v2, v2
	v_and_b32_e32 v2, 0xffff0000, v126
	v_fmac_f32_e32 v5, v2, v2
	v_lshlrev_b32_e32 v2, 16, v127
	v_fmac_f32_e32 v5, v2, v2
	v_and_b32_e32 v2, 0xffff0000, v127
	v_fmac_f32_e32 v5, v2, v2
	v_lshlrev_b32_e32 v2, 16, v128
	v_fmac_f32_e32 v5, v2, v2
	v_and_b32_e32 v2, 0xffff0000, v128
	v_fmac_f32_e32 v5, v2, v2
	v_lshlrev_b32_e32 v2, 16, v129
	v_fmac_f32_e32 v5, v2, v2
	v_and_b32_e32 v2, 0xffff0000, v129
	v_fmac_f32_e32 v5, v2, v2
	ds_bpermute_b32 v2, v197, v5
	v_sub_f32_e32 v6, v19, v18
	v_exp_f32_e32 v6, v6
	s_waitcnt lgkmcnt(0)
	v_add_f32_e32 v2, v5, v2
	v_mul_f32_e32 v5, 0x4f800000, v2
	v_cmp_gt_f32_e32 vcc, s71, v2
	v_ldexp_f32 v6, v6, s59
	v_mul_f32_e32 v190, 0x3fb8aa3b, v6
	v_cndmask_b32_e32 v2, v2, v5, vcc
	v_sqrt_f32_e32 v5, v2
	s_nop 0
	v_add_u32_e32 v6, -1, v5
	v_fma_f32 v7, -v6, v5, v2
	v_cmp_ge_f32_e64 s[4:5], 0, v7
	v_add_u32_e32 v7, 1, v5
	s_nop 0
	v_cndmask_b32_e64 v6, v5, v6, s[4:5]
	v_fma_f32 v5, -v7, v5, v2
	v_cmp_lt_f32_e64 s[4:5], 0, v5
	s_nop 1
	v_cndmask_b32_e64 v5, v6, v7, s[4:5]
	v_mul_f32_e32 v6, 0x37800000, v5
	v_cndmask_b32_e32 v5, v5, v6, vcc
	v_cmp_class_f32_e32 vcc, v2, v200
	s_nop 1
	v_cndmask_b32_e32 v2, v5, v2, vcc
	v_mul_f32_e32 v5, v201, v2
	v_fmaak_f32 v2, 2.0, v5, 0x42200000
	v_div_scale_f32 v6, s[4:5], v190, v190, v2
	v_rcp_f32_e32 v7, v6
	s_nop 0
	v_fma_f32 v8, -v6, v7, 1.0
	v_fmac_f32_e32 v7, v8, v7
	v_div_scale_f32 v8, vcc, v2, v190, v2
	v_mul_f32_e32 v9, v8, v7
	v_fma_f32 v10, -v6, v9, v8
	v_fmac_f32_e32 v9, v10, v7
	v_fma_f32 v6, -v6, v9, v8
	v_div_fmas_f32 v6, v6, v7, v9
	v_div_fixup_f32 v2, v6, v190, v2
	s_nop 1
	v_max_f32_dpp v2, v2, v2 quad_perm:[1,0,3,2] row_mask:0xf bank_mask:0xf
	s_nop 1
	v_max_f32_dpp v2, v2, v2 quad_perm:[2,3,0,1] row_mask:0xf bank_mask:0xf
	s_nop 1
	v_max_f32_dpp v2, v2, v2 row_half_mirror row_mask:0xf bank_mask:0xf
	s_nop 1
	v_max_f32_dpp v2, v2, v2 row_mirror row_mask:0xf bank_mask:0xf
	s_nop 1
	v_max_f32_dpp v2, v2, v2 row_bcast:15 row_mask:0xa bank_mask:0xf
	s_nop 1
	v_readlane_b32 s98, v2, 31
	s_and_saveexec_b64 s[4:5], s[0:1]
	s_cbranch_execz .LBB0_526
	s_nop 0
	v_mov_b32_e32 v2, s98
	v_mov_b32_e32 v6, s67
	ds_write_b32 v6, v2
